# sliding-window attention: the four gate-row loads of each step are issued together (one counted wait) instead of load-wait-store chains; on top of pipelined rope/residual epilogues, mLSTM fill rewrite
# speedup vs baseline: 1.0054x; 1.0001x over previous
.LBB0_657:
	v_or_b32_e32 v136, s23, v107
	v_cndmask_b32_e64 v140, v129, v48, s[6:7]
	v_or_b32_e32 v48, 2, v136
	v_cmp_gt_u32_e32 vcc, v48, v135
	s_and_b64 vcc, s[18:19], vcc
	v_or_b32_e32 v48, 3, v136
	v_cndmask_b32_e32 v142, v129, v50, vcc
	v_cmp_gt_u32_e32 vcc, v48, v135
	s_and_b64 vcc, s[18:19], vcc
	v_or_b32_e32 v48, 8, v136
	v_cndmask_b32_e32 v143, v129, v51, vcc
	v_cmp_gt_u32_e32 vcc, v48, v135
	s_and_b64 vcc, s[18:19], vcc
	v_or_b32_e32 v48, 9, v136
	v_cndmask_b32_e32 v144, v129, v52, vcc
	v_cmp_gt_u32_e32 vcc, v48, v135
	s_and_b64 vcc, s[18:19], vcc
	v_or_b32_e32 v48, 10, v136
	v_cndmask_b32_e32 v145, v129, v53, vcc
	v_cmp_gt_u32_e32 vcc, v48, v135
	s_and_b64 vcc, s[18:19], vcc
	v_or_b32_e32 v48, 11, v136
	v_cndmask_b32_e32 v146, v129, v54, vcc
	v_cmp_gt_u32_e32 vcc, v48, v135
	s_and_b64 vcc, s[18:19], vcc
	v_or_b32_e32 v48, 16, v136
	v_cndmask_b32_e32 v147, v129, v55, vcc
	v_cmp_gt_u32_e32 vcc, v48, v135
	s_and_b64 vcc, s[18:19], vcc
	v_or_b32_e32 v48, 17, v136
	v_cndmask_b32_e32 v148, v129, v56, vcc
	v_cmp_gt_u32_e32 vcc, v48, v135
	s_and_b64 vcc, s[18:19], vcc
	v_or_b32_e32 v48, 18, v136
	v_cndmask_b32_e32 v149, v129, v57, vcc
	v_cmp_gt_u32_e32 vcc, v48, v135
	s_and_b64 vcc, s[18:19], vcc
	v_or_b32_e32 v48, 19, v136
	v_cndmask_b32_e32 v150, v129, v58, vcc
	v_cmp_gt_u32_e32 vcc, v48, v135
	s_and_b64 vcc, s[18:19], vcc
	v_or_b32_e32 v48, 24, v136
	v_cndmask_b32_e32 v151, v129, v59, vcc
	v_cmp_gt_u32_e32 vcc, v48, v135
	s_and_b64 vcc, s[18:19], vcc
	v_or_b32_e32 v48, 25, v136
	v_cndmask_b32_e32 v152, v129, v60, vcc
	v_cmp_gt_u32_e32 vcc, v48, v135
	s_and_b64 vcc, s[18:19], vcc
	v_or_b32_e32 v48, 26, v136
	v_cndmask_b32_e32 v153, v129, v61, vcc
	v_cmp_gt_u32_e32 vcc, v48, v135
	v_cndmask_b32_e64 v141, v129, v49, s[8:9]
	s_and_b64 vcc, s[18:19], vcc
	v_or_b32_e32 v48, 27, v136
	v_cndmask_b32_e32 v154, v129, v62, vcc
	v_cmp_gt_u32_e32 vcc, v48, v135
	v_max3_f32 v48, v133, v140, v141
	v_max3_f32 v48, v48, v142, v143
	v_max3_f32 v48, v48, v144, v145
	v_max3_f32 v48, v48, v146, v147
	v_max3_f32 v48, v48, v148, v149
	s_and_b64 vcc, s[18:19], vcc
	v_max3_f32 v48, v48, v150, v151
	v_cndmask_b32_e32 v135, v129, v63, vcc
	v_max3_f32 v48, v48, v152, v153
	s_add_i32 s0, s25, 4
	v_max3_f32 v48, v48, v154, v135
	v_lshl_add_u32 v155, s0, 12, v106
	v_max3_f32 v52, v48, v0, v1
	v_add_u32_e32 v48, v155, v115
	ds_read_b128 v[48:51], v48
	v_max3_f32 v52, v52, v2, v3
	v_max3_f32 v52, v52, v4, v5
	v_max3_f32 v52, v52, v6, v7
	v_max3_f32 v52, v52, v8, v9
	v_max3_f32 v52, v52, v10, v11
	v_max3_f32 v156, v52, v12, v13
	v_add_u32_e32 v52, v155, v116
	ds_read_b128 v[136:139], v52
	s_waitcnt lgkmcnt(1)
	v_mfma_f32_32x32x16_bf16 v[48:63], v[48:51], v[68:71], 0
	v_max3_f32 v68, v156, v14, v15
	v_max3_f32 v68, v68, v32, v33
	v_max3_f32 v68, v68, v34, v35
	v_max3_f32 v68, v68, v36, v37
	v_max3_f32 v156, v68, v38, v39
	v_add_u32_e32 v68, v155, v117
	ds_read_b128 v[68:71], v68
	s_waitcnt lgkmcnt(1)
	v_mfma_f32_32x32x16_bf16 v[48:63], v[136:139], v[64:67], v[48:63]
	v_max3_f32 v64, v156, v40, v41
	v_max3_f32 v64, v64, v42, v43
	v_max3_f32 v64, v64, v44, v45
	v_max3_f32 v64, v64, v46, v47
	v_max3_f32 v136, v64, v16, v17
	v_add_u32_e32 v64, v155, v118
	ds_read_b128 v[64:67], v64
	s_waitcnt lgkmcnt(1)
	v_mfma_f32_32x32x16_bf16 v[48:63], v[68:71], v[76:79], v[48:63]
	s_lshl_b32 s0, s0, 5
	v_max3_f32 v68, v136, v18, v19
	v_max3_f32 v68, v68, v20, v21
	v_max3_f32 v68, v68, v22, v23
	v_max3_f32 v68, v68, v24, v25
	v_max3_f32 v68, v68, v26, v27
	v_max3_f32 v68, v68, v28, v29
	s_waitcnt lgkmcnt(0)
	v_mfma_f32_32x32x16_bf16 v[48:63], v[64:67], v[72:75], v[48:63]
	v_or_b32_e32 v64, s0, v107
	v_cmp_le_u32_e32 vcc, v64, v80
	v_max3_f32 v68, v68, v30, v31
	s_add_u32 s1, s20, s23
	s_nop 7
	v_cndmask_b32_e32 v65, v129, v48, vcc
	v_cmp_lt_u32_e32 vcc, v64, v80
	v_or_b32_e32 v48, 2, v64
	s_nop 0
	v_cndmask_b32_e32 v66, v129, v49, vcc
	v_cmp_le_u32_e32 vcc, v48, v80
	v_or_b32_e32 v48, 3, v64
	s_nop 0
	v_cndmask_b32_e32 v67, v129, v50, vcc
	v_cmp_le_u32_e32 vcc, v48, v80
	v_or_b32_e32 v48, 8, v64
	s_nop 0
	v_cndmask_b32_e32 v69, v129, v51, vcc
	v_cmp_le_u32_e32 vcc, v48, v80
	v_or_b32_e32 v48, 9, v64
	s_nop 0
	v_cndmask_b32_e32 v70, v129, v52, vcc
	v_cmp_le_u32_e32 vcc, v48, v80
	v_or_b32_e32 v48, 10, v64
	s_nop 0
	v_cndmask_b32_e32 v71, v129, v53, vcc
	v_cmp_le_u32_e32 vcc, v48, v80
	v_or_b32_e32 v48, 11, v64
	s_nop 0
	v_cndmask_b32_e32 v72, v129, v54, vcc
	v_cmp_le_u32_e32 vcc, v48, v80
	v_or_b32_e32 v48, 16, v64
	s_nop 0
	v_cndmask_b32_e32 v73, v129, v55, vcc
	v_cmp_le_u32_e32 vcc, v48, v80
	v_or_b32_e32 v48, 17, v64
	s_nop 0
	v_cndmask_b32_e32 v56, v129, v56, vcc
	v_cmp_le_u32_e32 vcc, v48, v80
	v_or_b32_e32 v48, 18, v64
	s_nop 0
	v_cndmask_b32_e32 v55, v129, v57, vcc
	v_cmp_le_u32_e32 vcc, v48, v80
	v_or_b32_e32 v48, 19, v64
	s_nop 0
	v_cndmask_b32_e32 v54, v129, v58, vcc
	v_cmp_le_u32_e32 vcc, v48, v80
	v_or_b32_e32 v48, 24, v64
	s_nop 0
	v_cndmask_b32_e32 v51, v129, v59, vcc
	v_cmp_le_u32_e32 vcc, v48, v80
	v_or_b32_e32 v48, 25, v64
	s_nop 0
	v_cndmask_b32_e32 v52, v129, v60, vcc
	v_cmp_le_u32_e32 vcc, v48, v80
	v_or_b32_e32 v48, 26, v64
	s_nop 0
	v_cndmask_b32_e32 v53, v129, v61, vcc
	v_cmp_le_u32_e32 vcc, v48, v80
	v_or_b32_e32 v48, 27, v64
	s_nop 0
	v_cndmask_b32_e32 v50, v129, v62, vcc
	v_cmp_le_u32_e32 vcc, v48, v80
	v_max3_f32 v48, v68, v65, v66
	v_max3_f32 v48, v48, v67, v69
	v_max3_f32 v48, v48, v70, v71
	v_max3_f32 v48, v48, v72, v73
	v_max3_f32 v48, v48, v56, v55
	v_max3_f32 v48, v48, v54, v51
	v_cndmask_b32_e32 v49, v129, v63, vcc
	v_max3_f32 v48, v48, v52, v53
	v_max3_f32 v48, v48, v50, v49
	ds_bpermute_b32 v57, v108, v48
	s_waitcnt lgkmcnt(0)
	v_max_f32_e32 v57, v57, v57
	v_max_f32_e32 v48, v48, v57
	v_sub_f32_e32 v57, v140, v48
	v_exp_f32_e32 v57, v57
	v_sub_f32_e32 v58, v141, v48
	v_exp_f32_e32 v58, v58
	v_sub_f32_e32 v60, v142, v48
	v_exp_f32_e32 v60, v60
	v_sub_f32_e32 v61, v143, v48
	v_exp_f32_e32 v61, v61
	v_sub_f32_e32 v62, v144, v48
	v_add_f32_e32 v59, 0, v57
	v_exp_f32_e32 v62, v62
	v_sub_f32_e32 v63, v145, v48
	v_add_f32_e32 v59, v58, v59
	v_exp_f32_e32 v63, v63
	v_sub_f32_e32 v64, v146, v48
	v_add_f32_e32 v59, v60, v59
	v_exp_f32_e32 v64, v64
	v_sub_f32_e32 v68, v147, v48
	v_add_f32_e32 v59, v61, v59
	v_exp_f32_e32 v68, v68
	v_sub_f32_e32 v74, v148, v48
	v_add_f32_e32 v59, v62, v59
	v_exp_f32_e32 v74, v74
	v_sub_f32_e32 v75, v149, v48
	v_add_f32_e32 v59, v63, v59
	v_exp_f32_e32 v75, v75
	v_sub_f32_e32 v76, v150, v48
	v_add_f32_e32 v59, v64, v59
	v_exp_f32_e32 v76, v76
	v_sub_f32_e32 v77, v151, v48
	v_add_f32_e32 v59, v68, v59
	v_exp_f32_e32 v77, v77
	v_sub_f32_e32 v78, v152, v48
	v_add_f32_e32 v59, v74, v59
	v_exp_f32_e32 v78, v78
	v_sub_f32_e32 v79, v153, v48
	v_add_f32_e32 v59, v75, v59
	v_exp_f32_e32 v79, v79
	v_sub_f32_e32 v80, v154, v48
	v_add_f32_e32 v59, v76, v59
	v_exp_f32_e32 v80, v80
	v_sub_f32_e32 v135, v135, v48
	v_add_f32_e32 v59, v77, v59
	v_exp_f32_e32 v135, v135
	v_sub_f32_e32 v0, v0, v48
	v_add_f32_e32 v59, v78, v59
	v_exp_f32_e32 v136, v0
	v_sub_f32_e32 v0, v1, v48
	v_add_f32_e32 v59, v79, v59
	v_exp_f32_e32 v137, v0
	v_sub_f32_e32 v1, v2, v48
	v_add_f32_e32 v0, v80, v59
	v_exp_f32_e32 v59, v1
	v_sub_f32_e32 v1, v3, v48
	v_add_f32_e32 v0, v135, v0
	v_exp_f32_e32 v138, v1
	v_sub_f32_e32 v1, v4, v48
	v_add_f32_e32 v0, v136, v0
	v_exp_f32_e32 v139, v1
	v_sub_f32_e32 v1, v5, v48
	v_add_f32_e32 v0, v137, v0
	v_exp_f32_e32 v140, v1
	v_sub_f32_e32 v1, v6, v48
	v_add_f32_e32 v0, v59, v0
	v_exp_f32_e32 v141, v1
	v_sub_f32_e32 v1, v7, v48
	v_add_f32_e32 v0, v138, v0
	v_exp_f32_e32 v142, v1
	v_sub_f32_e32 v1, v8, v48
	v_add_f32_e32 v0, v139, v0
	v_exp_f32_e32 v143, v1
	v_sub_f32_e32 v1, v9, v48
	v_add_f32_e32 v0, v140, v0
	v_exp_f32_e32 v144, v1
	v_sub_f32_e32 v1, v10, v48
	v_add_f32_e32 v0, v141, v0
	v_exp_f32_e32 v145, v1
	v_sub_f32_e32 v1, v11, v48
	v_add_f32_e32 v0, v142, v0
	v_exp_f32_e32 v146, v1
	v_sub_f32_e32 v1, v12, v48
	v_add_f32_e32 v0, v143, v0
	v_exp_f32_e32 v147, v1
	v_sub_f32_e32 v1, v13, v48
	v_add_f32_e32 v0, v144, v0
	v_exp_f32_e32 v148, v1
	v_sub_f32_e32 v1, v14, v48
	v_add_f32_e32 v0, v145, v0
	v_exp_f32_e32 v149, v1
	v_sub_f32_e32 v1, v15, v48
	v_add_f32_e32 v0, v146, v0
	v_exp_f32_e32 v150, v1
	v_sub_f32_e32 v1, v32, v48
	v_add_f32_e32 v0, v147, v0
	v_exp_f32_e32 v151, v1
	v_sub_f32_e32 v1, v33, v48
	v_add_f32_e32 v0, v148, v0
	v_exp_f32_e32 v152, v1
	v_sub_f32_e32 v1, v34, v48
	v_add_f32_e32 v0, v149, v0
	v_exp_f32_e32 v153, v1
	v_sub_f32_e32 v1, v35, v48
	v_add_f32_e32 v0, v150, v0
	v_exp_f32_e32 v154, v1
	v_sub_f32_e32 v1, v36, v48
	v_add_f32_e32 v0, v151, v0
	v_exp_f32_e32 v155, v1
	v_sub_f32_e32 v1, v37, v48
	v_add_f32_e32 v0, v152, v0
	v_exp_f32_e32 v156, v1
	v_sub_f32_e32 v1, v38, v48
	v_add_f32_e32 v0, v153, v0
	v_exp_f32_e32 v157, v1
	v_sub_f32_e32 v1, v39, v48
	v_add_f32_e32 v0, v154, v0
	v_exp_f32_e32 v158, v1
	v_sub_f32_e32 v1, v40, v48
	v_add_f32_e32 v0, v155, v0
	v_exp_f32_e32 v159, v1
	v_sub_f32_e32 v1, v41, v48
	v_add_f32_e32 v0, v156, v0
	v_exp_f32_e32 v160, v1
	v_sub_f32_e32 v1, v42, v48
	v_add_f32_e32 v0, v157, v0
	v_exp_f32_e32 v161, v1
	v_sub_f32_e32 v1, v43, v48
	v_add_f32_e32 v0, v158, v0
	v_exp_f32_e32 v162, v1
	v_sub_f32_e32 v1, v44, v48
	v_add_f32_e32 v0, v159, v0
	v_exp_f32_e32 v163, v1
	v_sub_f32_e32 v1, v45, v48
	v_add_f32_e32 v0, v160, v0
	v_exp_f32_e32 v164, v1
	v_sub_f32_e32 v1, v46, v48
	v_add_f32_e32 v0, v161, v0
	v_exp_f32_e32 v165, v1
	v_sub_f32_e32 v1, v47, v48
	v_add_f32_e32 v0, v162, v0
	v_exp_f32_e32 v166, v1
	v_sub_f32_e32 v1, v16, v48
	v_add_f32_e32 v0, v163, v0
	v_exp_f32_e32 v167, v1
	v_sub_f32_e32 v1, v17, v48
	v_add_f32_e32 v0, v164, v0
	v_exp_f32_e32 v168, v1
	v_sub_f32_e32 v1, v18, v48
	v_add_f32_e32 v0, v165, v0
	v_exp_f32_e32 v169, v1
	v_sub_f32_e32 v1, v19, v48
	v_add_f32_e32 v0, v166, v0
	v_exp_f32_e32 v170, v1
	v_sub_f32_e32 v1, v20, v48
	v_add_f32_e32 v0, v167, v0
	v_exp_f32_e32 v171, v1
	v_sub_f32_e32 v1, v21, v48
	v_add_f32_e32 v0, v168, v0
	v_exp_f32_e32 v172, v1
	v_sub_f32_e32 v1, v22, v48
	v_add_f32_e32 v0, v169, v0
	v_exp_f32_e32 v173, v1
	v_sub_f32_e32 v1, v23, v48
	v_add_f32_e32 v0, v170, v0
	v_exp_f32_e32 v174, v1
	v_sub_f32_e32 v1, v24, v48
	v_add_f32_e32 v0, v171, v0
	v_exp_f32_e32 v175, v1
	v_sub_f32_e32 v1, v25, v48
	v_add_f32_e32 v0, v172, v0
	v_exp_f32_e32 v176, v1
	v_add_f32_e32 v0, v173, v0
	v_add_f32_e32 v0, v174, v0
	v_add_f32_e32 v0, v175, v0
	v_add_f32_e32 v24, v176, v0
	v_sub_f32_e32 v0, v26, v48
	v_exp_f32_e32 v177, v0
	v_sub_f32_e32 v0, v27, v48
	v_exp_f32_e32 v178, v0
	v_or_b32_e32 v0, s23, v109
	v_lshlrev_b32_e32 v4, 1, v0
	v_lshlrev_b32_e32 v25, 7, v0
	v_and_b32_e32 v0, 4, v4
	v_or_b32_e32 v0, v0, v110
	v_bitop3_b32 v4, v4, v119, 4 bitop3:0x6c
	v_add_u32_e32 v5, v111, v25
	v_lshlrev_b32_e32 v26, 4, v0
	v_lshlrev_b32_e32 v27, 4, v4
	v_add_u32_e32 v2, v5, v26
	v_add_u32_e32 v4, v5, v27
	v_cvt_pk_bf16_f32 v16, v57, v58
	v_cvt_pk_bf16_f32 v17, v60, v61
	v_cvt_pk_bf16_f32 v18, v62, v63
	v_cvt_pk_bf16_f32 v19, v64, v68
	ds_read_b64_tr_b16 v[0:1], v2 offset:32768
	ds_read_b64_tr_b16 v[2:3], v2 offset:33792
	ds_read_b64_tr_b16 v[20:21], v4 offset:32768
	ds_read_b64_tr_b16 v[22:23], v4 offset:33792
	s_waitcnt lgkmcnt(2)
	v_mfma_f32_32x32x16_bf16 v[0:15], v[16:19], v[0:3], 0
	v_add_f32_e32 v24, v177, v24
	v_add_f32_e32 v57, v178, v24
	v_sub_f32_e32 v24, v28, v48
	v_exp_f32_e32 v28, v24
	v_sub_f32_e32 v24, v29, v48
	v_exp_f32_e32 v29, v24
	v_sub_f32_e32 v24, v30, v48
	s_waitcnt lgkmcnt(0)
	v_mfma_f32_32x32x16_bf16 v[32:47], v[16:19], v[20:23], 0
	v_or_b32_e32 v20, 0x800, v25
	v_add_u32_e32 v25, v111, v20
	v_add_u32_e32 v22, v25, v26
	v_cvt_pk_bf16_f32 v16, v74, v75
	v_cvt_pk_bf16_f32 v17, v76, v77
	v_cvt_pk_bf16_f32 v18, v78, v79
	v_cvt_pk_bf16_f32 v19, v80, v135
	ds_read_b64_tr_b16 v[20:21], v22 offset:32768
	ds_read_b64_tr_b16 v[22:23], v22 offset:33792
	v_add_u32_e32 v26, v25, v27
	v_exp_f32_e32 v30, v24
	ds_read_b64_tr_b16 v[24:25], v26 offset:32768
	ds_read_b64_tr_b16 v[26:27], v26 offset:33792
	s_waitcnt lgkmcnt(2)
	v_mfma_f32_32x32x16_bf16 v[0:15], v[16:19], v[20:23], v[0:15]
	v_add_f32_e32 v20, v28, v57
	v_add_f32_e32 v20, v29, v20
	v_add_f32_e32 v57, v30, v20
	v_sub_f32_e32 v20, v31, v48
	v_exp_f32_e32 v31, v20
	v_sub_f32_e32 v20, v65, v48
	v_exp_f32_e32 v58, v20
	s_waitcnt lgkmcnt(0)
	v_mfma_f32_32x32x16_bf16 v[32:47], v[16:19], v[24:27], v[32:47]
	v_cvt_pk_bf16_f32 v17, v59, v138
	v_lshlrev_b32_e32 v59, 7, v109
	v_lshl_or_b32 v20, s22, 12, v59
	v_lshlrev_b32_e32 v24, 1, v109
	v_add_u32_e32 v60, v111, v20
	v_and_b32_e32 v20, 4, v24
	v_or_b32_e32 v20, v20, v110
	v_lshlrev_b32_e32 v61, 4, v20
	v_bitop3_b32 v24, v24, v119, 4 bitop3:0x6c
	v_add_u32_e32 v22, v60, v61
	v_lshlrev_b32_e32 v62, 4, v24
	v_cvt_pk_bf16_f32 v16, v136, v137
	v_cvt_pk_bf16_f32 v18, v139, v140
	v_cvt_pk_bf16_f32 v19, v141, v142
	ds_read_b64_tr_b16 v[20:21], v22 offset:32768
	ds_read_b64_tr_b16 v[22:23], v22 offset:33792
	v_add_u32_e32 v26, v60, v62
	ds_read_b64_tr_b16 v[24:25], v26 offset:32768
	ds_read_b64_tr_b16 v[26:27], v26 offset:33792
	s_waitcnt lgkmcnt(2)
	v_mfma_f32_32x32x16_bf16 v[0:15], v[16:19], v[20:23], v[0:15]
	v_add_f32_e32 v20, v31, v57
	v_add_f32_e32 v57, v58, v20
	v_sub_f32_e32 v20, v66, v48
	v_exp_f32_e32 v63, v20
	v_sub_f32_e32 v20, v67, v48
	v_exp_f32_e32 v64, v20
	v_sub_f32_e32 v65, v69, v48
	s_waitcnt lgkmcnt(0)
	v_mfma_f32_32x32x16_bf16 v[32:47], v[16:19], v[24:27], v[32:47]
	v_add_u32_e32 v24, 0x800, v60
	v_add_u32_e32 v22, v24, v61
	v_cvt_pk_bf16_f32 v16, v143, v144
	v_cvt_pk_bf16_f32 v17, v145, v146
	v_cvt_pk_bf16_f32 v18, v147, v148
	v_cvt_pk_bf16_f32 v19, v149, v150
	ds_read_b64_tr_b16 v[20:21], v22 offset:32768
	ds_read_b64_tr_b16 v[22:23], v22 offset:33792
	v_exp_f32_e32 v60, v65
	v_add_u32_e32 v26, v24, v62
	s_waitcnt lgkmcnt(0)
	v_mfma_f32_32x32x16_bf16 v[0:15], v[16:19], v[20:23], v[0:15]
	v_sub_f32_e32 v20, v70, v48
	ds_read_b64_tr_b16 v[24:25], v26 offset:32768
	ds_read_b64_tr_b16 v[26:27], v26 offset:33792
	v_exp_f32_e32 v65, v20
	v_add_f32_e32 v20, v63, v57
	v_add_f32_e32 v20, v64, v20
	v_add_f32_e32 v20, v60, v20
	v_add_f32_e32 v57, v65, v20
	v_lshl_or_b32 v20, s24, 12, v59
	s_waitcnt lgkmcnt(0)
	v_mfma_f32_32x32x16_bf16 v[32:47], v[16:19], v[24:27], v[32:47]
	v_add_u32_e32 v59, v111, v20
	v_add_u32_e32 v22, v59, v61
	v_cvt_pk_bf16_f32 v16, v151, v152
	v_cvt_pk_bf16_f32 v17, v153, v154
	v_cvt_pk_bf16_f32 v18, v155, v156
	v_cvt_pk_bf16_f32 v19, v157, v158
	ds_read_b64_tr_b16 v[20:21], v22 offset:32768
	ds_read_b64_tr_b16 v[22:23], v22 offset:33792
	v_add_u32_e32 v26, v59, v62
	ds_read_b64_tr_b16 v[24:25], v26 offset:32768
	ds_read_b64_tr_b16 v[26:27], v26 offset:33792
	s_waitcnt lgkmcnt(2)
	v_mfma_f32_32x32x16_bf16 v[0:15], v[16:19], v[20:23], v[0:15]
	v_sub_f32_e32 v20, v72, v48
	v_exp_f32_e32 v67, v20
	v_sub_f32_e32 v20, v73, v48
	v_sub_f32_e32 v66, v71, v48
	v_exp_f32_e32 v68, v20
	v_sub_f32_e32 v20, v56, v48
	v_exp_f32_e32 v66, v66
	s_waitcnt lgkmcnt(0)
	v_mfma_f32_32x32x16_bf16 v[32:47], v[16:19], v[24:27], v[32:47]
	v_add_u32_e32 v24, 0x800, v59
	v_add_u32_e32 v22, v24, v61
	v_exp_f32_e32 v56, v20
	v_cvt_pk_bf16_f32 v16, v159, v160
	v_cvt_pk_bf16_f32 v17, v161, v162
	v_cvt_pk_bf16_f32 v18, v163, v164
	v_cvt_pk_bf16_f32 v19, v165, v166
	ds_read_b64_tr_b16 v[20:21], v22 offset:32768
	ds_read_b64_tr_b16 v[22:23], v22 offset:33792
	v_sub_f32_e32 v55, v55, v48
	v_add_f32_e32 v57, v66, v57
	v_add_u32_e32 v26, v24, v62
	v_exp_f32_e32 v55, v55
	ds_read_b64_tr_b16 v[24:25], v26 offset:32768
	ds_read_b64_tr_b16 v[26:27], v26 offset:33792
	s_waitcnt lgkmcnt(2)
	v_mfma_f32_32x32x16_bf16 v[0:15], v[16:19], v[20:23], v[0:15]
	v_add_f32_e32 v20, v67, v57
	v_add_f32_e32 v20, v68, v20
	v_add_f32_e32 v20, v56, v20
	v_add_f32_e32 v57, v55, v20
	v_sub_f32_e32 v20, v54, v48
	v_exp_f32_e32 v54, v20
	v_or_b32_e32 v20, s10, v109
	s_waitcnt lgkmcnt(0)
	v_mfma_f32_32x32x16_bf16 v[32:47], v[16:19], v[24:27], v[32:47]
	v_lshlrev_b32_e32 v24, 1, v20
	v_lshlrev_b32_e32 v59, 7, v20
	v_and_b32_e32 v20, 4, v24
	v_or_b32_e32 v20, v20, v110
	v_add_u32_e32 v25, v111, v59
	v_lshlrev_b32_e32 v69, 4, v20
	v_bitop3_b32 v24, v24, v119, 4 bitop3:0x6c
	v_add_u32_e32 v22, v25, v69
	v_lshlrev_b32_e32 v70, 4, v24
	v_cvt_pk_bf16_f32 v16, v167, v168
	v_cvt_pk_bf16_f32 v17, v169, v170
	v_cvt_pk_bf16_f32 v18, v171, v172
	v_cvt_pk_bf16_f32 v19, v173, v174
	ds_read_b64_tr_b16 v[20:21], v22 offset:32768
	ds_read_b64_tr_b16 v[22:23], v22 offset:33792
	v_add_u32_e32 v26, v25, v70
	ds_read_b64_tr_b16 v[24:25], v26 offset:32768
	ds_read_b64_tr_b16 v[26:27], v26 offset:33792
	s_waitcnt lgkmcnt(2)
	v_mfma_f32_32x32x16_bf16 v[0:15], v[16:19], v[20:23], v[0:15]
	v_sub_f32_e32 v20, v51, v48
	s_addc_u32 s10, s21, 0
	v_exp_f32_e32 v51, v20
	v_sub_f32_e32 v20, v52, v48
	v_exp_f32_e32 v71, v20
	v_sub_f32_e32 v20, v53, v48
	v_exp_f32_e32 v72, v20
	s_waitcnt lgkmcnt(0)
	v_mfma_f32_32x32x16_bf16 v[32:47], v[16:19], v[24:27], v[32:47]
	v_cvt_pk_bf16_f32 v18, v28, v29
	v_mov_b32_e32 v29, s10
	v_or_b32_e32 v28, s1, v86
	v_lshlrev_b64 v[28:29], 11, v[28:29]
	v_or_b32_e32 v20, 0x800, v59
	v_lshl_add_u64 v[28:29], v[28:29], 0, v[96:97]
	v_add_u32_e32 v20, v111, v20
	v_lshlrev_b64 v[52:53], 1, v[28:29]
	v_add_u32_e32 v22, v20, v69
	v_add_u32_e32 v26, v20, v70
	v_lshl_add_u64 v[28:29], s[12:13], 0, v[52:53]
	v_cvt_pk_bf16_f32 v19, v30, v31
	ds_read_b64_tr_b16 v[20:21], v22 offset:32768
	ds_read_b64_tr_b16 v[22:23], v22 offset:33792
	ds_read_b64_tr_b16 v[24:25], v26 offset:32768
	ds_read_b64_tr_b16 v[26:27], v26 offset:33792
	global_load_dwordx4 v[28:31], v[28:29], off
	v_mov_b32_e32 v193, s10
	v_or_b32_e32 v192, s1, v88
	v_lshlrev_b64 v[192:193], 11, v[192:193]
	v_lshl_add_u64 v[192:193], v[192:193], 0, v[96:97]
	v_lshlrev_b64 v[192:193], 1, v[192:193]
	v_lshl_add_u64 v[192:193], s[12:13], 0, v[192:193]
	global_load_dwordx4 v[180:183], v[192:193], off
	v_mov_b32_e32 v193, s10
	v_or_b32_e32 v192, s1, v90
	v_lshlrev_b64 v[192:193], 11, v[192:193]
	v_lshl_add_u64 v[192:193], v[192:193], 0, v[96:97]
	v_lshlrev_b64 v[192:193], 1, v[192:193]
	v_lshl_add_u64 v[192:193], s[12:13], 0, v[192:193]
	global_load_dwordx4 v[184:187], v[192:193], off
	v_mov_b32_e32 v193, s10
	v_or_b32_e32 v192, s1, v92
	v_lshlrev_b64 v[192:193], 11, v[192:193]
	v_lshl_add_u64 v[192:193], v[192:193], 0, v[96:97]
	v_lshlrev_b64 v[192:193], 1, v[192:193]
	v_lshl_add_u64 v[192:193], s[12:13], 0, v[192:193]
	global_load_dwordx4 v[188:191], v[192:193], off
	v_cvt_pk_bf16_f32 v16, v175, v176
	v_cvt_pk_bf16_f32 v17, v177, v178
	v_add_f32_e32 v57, v54, v57
	v_sub_f32_e32 v49, v49, v48
	s_waitcnt lgkmcnt(2)
	v_mfma_f32_32x32x16_bf16 v[0:15], v[16:19], v[20:23], v[0:15]
	v_sub_f32_e32 v20, v50, v48
	v_exp_f32_e32 v50, v20
	v_add_f32_e32 v20, v51, v57
	v_add_f32_e32 v20, v71, v20
	v_add_f32_e32 v20, v72, v20
	v_add_f32_e32 v57, v50, v20
	v_or_b32_e32 v20, s0, v109
	s_waitcnt lgkmcnt(0)
	v_mfma_f32_32x32x16_bf16 v[32:47], v[16:19], v[24:27], v[32:47]
	v_cvt_pk_bf16_f32 v16, v58, v63
	v_lshl_add_u32 v58, v20, 7, v111
	v_add_u32_e32 v22, v58, v61
	v_cvt_pk_bf16_f32 v17, v64, v60
	v_cvt_pk_bf16_f32 v18, v65, v66
	v_cvt_pk_bf16_f32 v19, v67, v68
	ds_read_b64_tr_b16 v[20:21], v22 offset:32768
	ds_read_b64_tr_b16 v[22:23], v22 offset:33792
	v_exp_f32_e32 v49, v49
	v_add_u32_e32 v26, v58, v62
	s_waitcnt lgkmcnt(0)
	v_mfma_f32_32x32x16_bf16 v[0:15], v[16:19], v[20:23], v[0:15]
	v_add_f32_e32 v20, v49, v57
	ds_read_b64_tr_b16 v[24:25], v26 offset:32768
	ds_read_b64_tr_b16 v[26:27], v26 offset:33792
	ds_bpermute_b32 v21, v108, v20
	v_sub_f32_e32 v22, v133, v48
	v_exp_f32_e32 v48, v22
	s_cmp_lg_u32 s22, 4
	s_waitcnt lgkmcnt(0)
	v_add_f32_e32 v57, v20, v21
	v_mfma_f32_32x32x16_bf16 v[32:47], v[16:19], v[24:27], v[32:47]
	v_add_u32_e32 v24, 0x800, v58
	v_add_u32_e32 v22, v24, v61
	v_add_f32_e32 v48, v48, v57
	v_cvt_pk_bf16_f32 v16, v56, v55
	v_cvt_pk_bf16_f32 v17, v54, v51
	v_cvt_pk_bf16_f32 v18, v71, v72
	v_cvt_pk_bf16_f32 v19, v50, v49
	ds_read_b64_tr_b16 v[20:21], v22 offset:32768
	ds_read_b64_tr_b16 v[22:23], v22 offset:33792
	v_div_scale_f32 v49, s[24:25], v48, v48, 1.0
	v_rcp_f32_e32 v50, v49
	v_add_u32_e32 v26, v24, v62
	s_waitcnt lgkmcnt(0)
	v_mfma_f32_32x32x16_bf16 v[0:15], v[16:19], v[20:23], v[0:15]
	ds_read_b64_tr_b16 v[24:25], v26 offset:32768
	ds_read_b64_tr_b16 v[26:27], v26 offset:33792
	v_fma_f32 v20, -v49, v50, 1.0
	v_fmac_f32_e32 v50, v20, v50
	v_div_scale_f32 v20, vcc, 1.0, v48, 1.0
	v_mul_f32_e32 v21, v20, v50
	v_fma_f32 v22, -v49, v21, v20
	v_fmac_f32_e32 v21, v22, v50
	v_fma_f32 v20, -v49, v21, v20
	v_div_fmas_f32 v20, v20, v50, v21
	s_waitcnt lgkmcnt(0)
	v_mfma_f32_32x32x16_bf16 v[32:47], v[16:19], v[24:27], v[32:47]
	v_div_fixup_f32 v20, v20, v48, 1.0
	ds_write_b32 v112, v20
	ds_read_b128 v[20:23], v128
	ds_read_b128 v[16:19], v128 offset:32
	ds_read_b128 v[24:27], v128 offset:64
	ds_read_b128 v[48:51], v128 offset:96
	s_mov_b32 s25, s22
	s_waitcnt lgkmcnt(2)
	v_mul_f32_e32 v4, v4, v16
	v_mul_f32_e32 v0, v0, v20
	s_nop 1
	v_mul_f32_e32 v20, v32, v20
	v_mul_f32_e32 v1, v1, v21
	ds_write2_b32 v95, v0, v20 offset1:32
	v_mul_f32_e32 v0, v33, v21
	v_mul_f32_e32 v2, v2, v22
	ds_write2_b32 v95, v1, v0 offset0:64 offset1:96
	v_mul_f32_e32 v0, v34, v22
	v_mul_f32_e32 v3, v3, v23
	ds_write2_b32 v95, v2, v0 offset0:128 offset1:160
	v_mul_f32_e32 v0, v35, v23
	ds_write2_b32 v95, v3, v0 offset0:192 offset1:224
	ds_read_b128 v[0:3], v130
	ds_read_b128 v[20:23], v130 offset:16
	s_waitcnt vmcnt(0)
	v_lshlrev_b32_e32 v32, 16, v28
	v_and_b32_e32 v33, 0xffff0000, v28
	v_lshlrev_b32_e32 v28, 16, v29
	v_and_b32_e32 v29, 0xffff0000, v29
	s_waitcnt lgkmcnt(1)
	v_pk_mul_f32 v[0:1], v[0:1], v[32:33]
	v_pk_mul_f32 v[2:3], v[2:3], v[28:29]
	v_cvt_pk_bf16_f32 v0, v0, v1
	v_cvt_pk_bf16_f32 v1, v2, v3
	v_lshlrev_b32_e32 v2, 16, v30
	v_and_b32_e32 v3, 0xffff0000, v30
	s_waitcnt lgkmcnt(0)
	v_pk_mul_f32 v[2:3], v[20:21], v[2:3]
	v_lshlrev_b32_e32 v20, 16, v31
	v_and_b32_e32 v21, 0xffff0000, v31
	v_pk_mul_f32 v[20:21], v[22:23], v[20:21]
	v_cvt_pk_bf16_f32 v2, v2, v3
	v_cvt_pk_bf16_f32 v3, v20, v21
	v_lshl_add_u64 v[20:21], s[50:51], 0, v[52:53]
	global_store_dwordx4 v[20:21], v[0:3], off
	v_mul_f32_e32 v16, v36, v16
	v_add_u32_e32 v22, 0x800, v95
	v_mov_b32_e32 v1, s10
	v_or_b32_e32 v0, s1, v88
	v_lshlrev_b64 v[0:1], 11, v[0:1]
	v_lshl_add_u64 v[0:1], v[0:1], 0, v[96:97]
	v_lshlrev_b64 v[20:21], 1, v[0:1]
	v_lshl_add_u64 v[0:1], s[12:13], 0, v[20:21]
	v_mul_f32_e32 v5, v5, v17
	ds_write2_b32 v22, v4, v16 offset1:32
	v_mul_f32_e32 v4, v37, v17
	v_mul_f32_e32 v6, v6, v18
	ds_write2_b32 v22, v5, v4 offset0:64 offset1:96
	v_mul_f32_e32 v4, v38, v18
	v_mul_f32_e32 v7, v7, v19
	ds_write2_b32 v22, v6, v4 offset0:128 offset1:160
	v_mul_f32_e32 v4, v39, v19
	ds_write2_b32 v22, v7, v4 offset0:192 offset1:224
	ds_read_b128 v[4:7], v131
	ds_read_b128 v[16:19], v131 offset:16
	v_lshlrev_b32_e32 v22, 16, v180
	v_and_b32_e32 v23, 0xffff0000, v180
	s_waitcnt lgkmcnt(1)
	v_pk_mul_f32 v[4:5], v[4:5], v[22:23]
	s_nop 0
	v_cvt_pk_bf16_f32 v0, v4, v5
	v_lshlrev_b32_e32 v4, 16, v181
	v_and_b32_e32 v5, 0xffff0000, v181
	v_pk_mul_f32 v[4:5], v[6:7], v[4:5]
	v_mul_f32_e32 v6, v10, v26
	v_cvt_pk_bf16_f32 v1, v4, v5
	v_lshlrev_b32_e32 v4, 16, v182
	v_and_b32_e32 v5, 0xffff0000, v182
	s_waitcnt lgkmcnt(0)
	v_pk_mul_f32 v[4:5], v[16:17], v[4:5]
	v_mul_f32_e32 v7, v11, v27
	v_cvt_pk_bf16_f32 v2, v4, v5
	v_lshlrev_b32_e32 v4, 16, v183
	v_and_b32_e32 v5, 0xffff0000, v183
	v_pk_mul_f32 v[4:5], v[18:19], v[4:5]
	s_nop 0
	v_cvt_pk_bf16_f32 v3, v4, v5
	v_lshl_add_u64 v[4:5], s[50:51], 0, v[20:21]
	global_store_dwordx4 v[4:5], v[0:3], off
	v_mul_f32_e32 v4, v8, v24
	v_mul_f32_e32 v5, v9, v25
	v_mov_b32_e32 v1, s10
	v_or_b32_e32 v0, s1, v90
	v_lshlrev_b64 v[0:1], 11, v[0:1]
	v_lshl_add_u64 v[0:1], v[0:1], 0, v[96:97]
	v_lshlrev_b64 v[16:17], 1, v[0:1]
	v_lshl_add_u64 v[0:1], s[12:13], 0, v[16:17]
	v_mul_f32_e32 v8, v40, v24
	v_add_u32_e32 v9, 0x1000, v95
	ds_write2_b32 v9, v4, v8 offset1:32
	v_mul_f32_e32 v4, v41, v25
	ds_write2_b32 v9, v5, v4 offset0:64 offset1:96
	v_mul_f32_e32 v4, v42, v26
	ds_write2_b32 v9, v6, v4 offset0:128 offset1:160
	v_mul_f32_e32 v4, v43, v27
	ds_write2_b32 v9, v7, v4 offset0:192 offset1:224
	ds_read_b128 v[4:7], v132
	ds_read_b128 v[8:11], v132 offset:16
	v_lshlrev_b32_e32 v18, 16, v184
	v_and_b32_e32 v19, 0xffff0000, v184
	s_waitcnt lgkmcnt(1)
	v_pk_mul_f32 v[4:5], v[4:5], v[18:19]
	s_nop 0
	v_cvt_pk_bf16_f32 v0, v4, v5
	v_lshlrev_b32_e32 v4, 16, v185
	v_and_b32_e32 v5, 0xffff0000, v185
	v_pk_mul_f32 v[4:5], v[6:7], v[4:5]
	v_mul_f32_e32 v6, v14, v50
	v_cvt_pk_bf16_f32 v1, v4, v5
	v_lshlrev_b32_e32 v4, 16, v186
	v_and_b32_e32 v5, 0xffff0000, v186
	s_waitcnt lgkmcnt(0)
	v_pk_mul_f32 v[4:5], v[8:9], v[4:5]
	v_mul_f32_e32 v8, v44, v48
	v_cvt_pk_bf16_f32 v2, v4, v5
	v_lshlrev_b32_e32 v4, 16, v187
	v_and_b32_e32 v5, 0xffff0000, v187
	v_pk_mul_f32 v[4:5], v[10:11], v[4:5]
	v_add_u32_e32 v9, 0x1800, v95
	v_cvt_pk_bf16_f32 v3, v4, v5
	v_lshl_add_u64 v[4:5], s[50:51], 0, v[16:17]
	global_store_dwordx4 v[4:5], v[0:3], off
	v_mul_f32_e32 v4, v12, v48
	v_mul_f32_e32 v5, v13, v49
	v_mov_b32_e32 v1, s10
	v_or_b32_e32 v0, s1, v92
	v_lshlrev_b64 v[0:1], 11, v[0:1]
	v_lshl_add_u64 v[0:1], v[0:1], 0, v[96:97]
	v_lshlrev_b64 v[16:17], 1, v[0:1]
	v_lshl_add_u64 v[0:1], s[12:13], 0, v[16:17]
	ds_write2_b32 v9, v4, v8 offset1:32
	v_mul_f32_e32 v4, v45, v49
	ds_write2_b32 v9, v5, v4 offset0:64 offset1:96
	v_mul_f32_e32 v4, v46, v50
	v_mul_f32_e32 v7, v15, v51
	ds_write2_b32 v9, v6, v4 offset0:128 offset1:160
	v_mul_f32_e32 v4, v47, v51
	ds_write2_b32 v9, v7, v4 offset0:192 offset1:224
	ds_read_b128 v[4:7], v134
	ds_read_b128 v[8:11], v134 offset:16
	v_lshlrev_b32_e32 v12, 16, v188
	v_and_b32_e32 v13, 0xffff0000, v188
	s_waitcnt lgkmcnt(1)
	v_pk_mul_f32 v[4:5], v[4:5], v[12:13]
	s_nop 0
	v_cvt_pk_bf16_f32 v0, v4, v5
	v_lshlrev_b32_e32 v4, 16, v189
	v_and_b32_e32 v5, 0xffff0000, v189
	v_pk_mul_f32 v[4:5], v[6:7], v[4:5]
	s_nop 0
	v_cvt_pk_bf16_f32 v1, v4, v5
	v_lshlrev_b32_e32 v4, 16, v190
	v_and_b32_e32 v5, 0xffff0000, v190
	s_waitcnt lgkmcnt(0)
	v_pk_mul_f32 v[4:5], v[8:9], v[4:5]
	s_nop 0
	v_cvt_pk_bf16_f32 v2, v4, v5
	v_lshlrev_b32_e32 v4, 16, v191
	v_and_b32_e32 v5, 0xffff0000, v191
	v_pk_mul_f32 v[4:5], v[10:11], v[4:5]
	s_nop 0
	v_cvt_pk_bf16_f32 v3, v4, v5
	v_lshl_add_u64 v[4:5], s[50:51], 0, v[16:17]
	global_store_dwordx4 v[4:5], v[0:3], off
	s_cbranch_scc0 .LBB0_651
